# attention: softmax denominators by scalar f32 adds of the exp outputs (no ones-column MFMA)
# baseline (speedup 1.0000x reference)
; #define LAS __attribute__((address_space(3)))
; __device__ __forceinline__ int otid() { int t = threadIdx.x; asm volatile("" : "+v"(t)); return t; }
; #define WBAR() do { asm volatile("s_waitcnt vmcnt(0) lgkmcnt(0)" ::: "memory"); __builtin_amdgcn_s_barrier(); asm volatile("" ::: "memory"); } while (0)
; __device__ __forceinline__ void attn_unit(const unsigned char* __restrict__ Qb, const unsigned char* __restrict__ Kh, const unsigned char* __restrict__ VTh, f16* __restrict__ Ob, int seq, LAS char* lds) {
;     const int tid = otid(), wid = __builtin_amdgcn_readfirstlane(tid >> 6), lane = tid & 63, r32 = lane & 31, hi = lane >> 5;
;     LAS float* ws = (LAS float*)(lds + WS8) + wid * 64; LAS float* li_l = ws; LAS float* al_l = ws + 32;
;     f32x16 o[5] = {}; v8i qf[3]; f32x16 negm;
; #pragma unroll
;     for (int r = 0; r < 16; ++r) negm[r] = SH;
;     const unsigned char* Qw = Qb + (long)(wid * 32 + r32) * LDQ + hi * 32;
; #pragma unroll
;     for (int st = 0; st < 3; ++st) { const v4i x = *(const v4i*)(Qw + 64 * st), y = *(const v4i*)(Qw + 64 * st + 16); qf[st] = (v8i){x[0], x[1], x[2], x[3], y[0], y[1], y[2], y[3]}; }
;     const int sw = (r32 >> 2) & 3;
;     const int ka0 = r32 * 192 + (((2 * hi) ^ sw) << 4), ka1 = r32 * 192 + (((2 * hi + 1) ^ sw) << 4);
;     const int va0 = r32 * 64 + (((2 * hi) ^ sw) << 4), va1 = r32 * 64 + (((2 * hi + 1) ^ sw) << 4);
;     ...
;     f32x16 pA0, pA1, pB0, pB1; float dlA, dlB, alA, alB; v8i pa; const int NT = seq / 64;
;     const int NS = NT >> 1;
;     WBAR();
;     ISSUE(0);
;     WBAR();
;     if (1 < NS) ISSUE(1);
;     qkt(pA0, pA1, KSL(0), ka0, ka1, qf, negm); partialSM<true>(pA0, pA1, negm, dlA, alA);
.LBB0_586:
	v_lshrrev_b32_e32 v0, 2, v2
	v_bfe_u32 v2, v2, 2, 2
	v_lshlrev_b32_e32 v3, 1, v239
	v_bitop3_b32 v0, v3, v0, 3 bitop3:0x78
	v_bitop3_b32 v2, v3, v2, 1 bitop3:0x36
	v_lshlrev_b32_e32 v0, 4, v0
	v_lshlrev_b32_e32 v58, 4, v2
	v_mul_u32_u24_e32 v2, 0xc0, v238
	v_or_b32_e32 v244, v0, v2
	s_add_i32 m0, s15, 0
	v_or_b32_e32 v245, v58, v2
	global_load_lds_dwordx4 v4, s[0:1]
	v_add_u32_e32 v59, 0, v244
	v_add_u32_e32 v60, 0, v245
	ds_read_b128 v[2:5], v59 offset:49152
	ds_read_b128 v[6:9], v60 offset:49152
	v_readlane_b32 s68, v253, 62
	v_readlane_b32 s69, v253, 63
	v_readlane_b32 s70, v254, 0
	v_readlane_b32 s71, v254, 1
	v_readlane_b32 s72, v254, 2
	v_readlane_b32 s73, v254, 3
	v_readlane_b32 s74, v254, 4
	v_readlane_b32 s75, v254, 5
	v_readlane_b32 s76, v254, 6
	v_readlane_b32 s77, v254, 7
	v_readlane_b32 s78, v254, 8
	v_readlane_b32 s79, v254, 9
	v_readlane_b32 s80, v254, 10
	v_readlane_b32 s81, v254, 11
	v_readlane_b32 s82, v254, 12
	v_readlane_b32 s83, v254, 13
	s_mov_b32 s69, s68
	s_mov_b32 s70, s68
	s_mov_b32 s71, s68
	s_mov_b32 s72, s68
	s_mov_b32 s73, s68
	s_mov_b32 s74, s68
	s_mov_b32 s75, s68
	s_mov_b32 s76, s68
	s_mov_b32 s77, s68
	s_mov_b32 s78, s68
	s_mov_b32 s79, s68
	s_mov_b32 s80, s68
	s_mov_b32 s81, s68
	s_mov_b32 s82, s68
	s_mov_b32 s83, s68
	v_mov_b64_e32 v[18:19], s[68:69]
	v_mov_b64_e32 v[20:21], s[70:71]
	v_mov_b64_e32 v[22:23], s[72:73]
	v_mov_b64_e32 v[24:25], s[74:75]
	v_mov_b64_e32 v[26:27], s[76:77]
	v_mov_b64_e32 v[28:29], s[78:79]
	v_mov_b64_e32 v[30:31], s[80:81]
	v_mov_b64_e32 v[32:33], s[82:83]
	ds_read_b128 v[34:37], v59 offset:49216
	ds_read_b128 v[38:41], v60 offset:49216
	s_waitcnt vmcnt(0) lgkmcnt(0)
	v_mfma_scale_f32_32x32x64_f8f6f4 v[2:17], v[2:9], v[184:191], v[18:33], v234, v233 op_sel_hi:[0,0,0]
	ds_read_b128 v[46:49], v60 offset:55296
	ds_read_b128 v[42:45], v59 offset:55296
	ds_read_b128 v[50:53], v59 offset:49280
	ds_read_b128 v[54:57], v60 offset:49280
	s_mov_b32 s0, s68
	v_writelane_b32 v253, s0, 62
	s_lshl_b32 s28, s2, 13
	s_add_i32 s28, s28, s17
	v_writelane_b32 v254, s2, 0
	v_writelane_b32 v254, s3, 1
	v_writelane_b32 v254, s4, 2
	v_writelane_b32 v254, s5, 3
	v_writelane_b32 v254, s6, 4
	v_writelane_b32 v254, s7, 5
	v_writelane_b32 v254, s8, 6
	v_writelane_b32 v254, s9, 7
	v_writelane_b32 v254, s10, 8
	v_writelane_b32 v254, s11, 9
	s_waitcnt lgkmcnt(2)
	v_mfma_scale_f32_32x32x64_f8f6f4 v[18:33], v[42:49], v[184:191], v[18:33], v234, v233 op_sel_hi:[0,0,0]
	v_writelane_b32 v254, s12, 10
	v_writelane_b32 v254, s13, 11
	v_writelane_b32 v254, s14, 12
	v_writelane_b32 v254, s15, 13
	s_and_b32 s0, s14, 0x3fffffc0
	s_lshl_b32 s0, s0, 2
	s_add_i32 s20, s0, 0
	s_lshl_b32 s0, s2, 12
	s_lshl_b32 s35, s16, 13
	s_add_i32 s29, s28, s0
	s_add_i32 s35, s35, s19
	s_lshl_b32 s0, s16, 12
	s_lshl_b32 s26, s18, 13
	s_lshl_b32 s22, s2, 6
	s_add_i32 s2, s35, s0
	v_mfma_scale_f32_32x32x64_f8f6f4 v[2:17], v[34:41], v[176:183], v[2:17], v234, v233 op_sel_hi:[0,0,0]
	ds_read_b128 v[38:41], v60 offset:55360
	ds_read_b128 v[34:37], v59 offset:55360
	ds_read_b128 v[42:45], v59 offset:55424
	ds_read_b128 v[46:49], v60 offset:55424
	s_add_i32 s26, s26, s46
	s_lshl_b32 s0, s18, 12
	s_lshl_b32 s31, s33, 13
	s_add_i32 s20, s20, 0x18000
	s_add_i32 s27, s26, s0
	s_add_i32 s31, s31, s50
	s_lshl_b32 s0, s33, 12
	v_or_b32_e32 v246, 0x3800, v58
	v_or_b32_e32 v248, 0x3000, v58
	v_or_b32_e32 v249, 0x2800, v58
	v_or_b32_e32 v250, 0x2000, v58
	v_or_b32_e32 v251, 0x3800, v0
	v_or_b32_e32 v252, 0x3000, v0
	v_or_b32_e32 v231, 0x2800, v0
	s_waitcnt lgkmcnt(2)
	v_mfma_scale_f32_32x32x64_f8f6f4 v[18:33], v[34:41], v[176:183], v[18:33], v234, v233 op_sel_hi:[0,0,0]
	v_lshlrev_b32_e32 v34, 6, v238
	v_or_b32_e32 v240, v58, v34
	v_or_b32_e32 v241, v0, v34
	v_add_u32_e32 v247, 0, v34
	v_or_b32_e32 v218, 0x2000, v0
	v_mov_b32_e32 v0, v1
	v_writelane_b32 v253, s1, 63
	s_mov_b32 s21, 2
	s_lshr_b32 s47, s3, 6
	s_lshr_b32 s14, s3, 7
	s_mov_b32 s15, 0
	v_cmp_eq_u32_e64 s[12:13], 0, v239
	v_lshl_add_u32 v243, v238, 2, s20
	v_lshlrev_b32_e32 v242, 4, v239
	s_lshl_b32 s34, s16, 6
	v_mfma_scale_f32_32x32x64_f8f6f4 v[2:17], v[50:57], v[168:175], v[2:17], v234, v233 op_sel_hi:[0,0,0]
	s_lshl_b32 s3, s18, 6
	s_lshl_b32 s30, s33, 6
	s_add_i32 s49, s31, s0
	s_lshl_b32 s16, s42, 6
	s_add_i32 s18, s38, s51
	s_add_i32 s33, s39, s51
	s_mov_b32 s68, 0xfffe5000
	s_mov_b32 s69, 0xfffe6000
	s_mov_b32 s70, 0xfffe7000
	s_mov_b32 s71, 0xfffe8000
	s_mov_b32 s72, 0xfffe9000
	s_mov_b32 s73, 0xfffea000
	s_mov_b32 s74, 0xfffeb000
	s_mov_b32 s75, 0xfffec000
	s_mov_b32 s76, 0xfffed000
	s_waitcnt lgkmcnt(0)
; template <bool FIRST>
; __device__ __forceinline__ void partialSM(f32x16& p0, f32x16& p1, f32x16& negm, float& dl, float& alpha) {
;     float pmax = p0[0];
; #pragma unroll
;     for (int r = 1; r < 16; ++r) pmax = fmaxf(pmax, p0[r]);
; #pragma unroll
;     for (int r = 0; r < 16; ++r) pmax = fmaxf(pmax, p1[r]);
;     { auto rr = __builtin_amdgcn_permlane32_swap(__float_as_uint(pmax), __float_as_uint(pmax), false, false);
;       pmax = fmaxf(__uint_as_float(rr[0]), __uint_as_float(rr[1])); }
;     if (FIRST) {
;         dl = 0.f; alpha = 1.f; const float d0_ = pmax - SH;
; #pragma unroll
;         for (int r = 0; r < 16; ++r) { p0[r] -= d0_; p1[r] -= d0_; negm[r] -= d0_; }
;     } else {
;         const bool keep = __all(pmax <= SH + THRL);
;         dl = keep ? 0.f : fmaxf(pmax - SH, 0.f); alpha = __builtin_amdgcn_exp2f(-dl);
;     }
; #pragma unroll
;     for (int r = 0; r < 16; ++r) p0[r] = __builtin_amdgcn_exp2f(p0[r]);
	v_mfma_scale_f32_32x32x64_f8f6f4 v[18:33], v[42:49], v[168:175], v[18:33], v234, v233 op_sel_hi:[0,0,0]
	s_nop 2
	v_max_f32_e32 v35, v3, v3
	v_max_f32_e32 v36, v2, v2
	v_max_f32_e32 v35, v36, v35
	v_max3_f32 v35, v35, v4, v5
	v_max3_f32 v35, v35, v6, v7
	v_max3_f32 v35, v35, v8, v9
	v_max3_f32 v35, v35, v10, v11
	v_max3_f32 v35, v35, v12, v13
	v_max3_f32 v35, v35, v14, v15
	v_max3_f32 v35, v35, v16, v17
	s_mov_b32 s77, 0xfffee000
	s_mov_b32 s78, 0xfffef000
	s_mov_b32 s79, 0xffff0000
	s_mov_b32 s80, 0xffff1000
	s_mov_b32 s81, 0xffff2000
	s_nop 1
	v_max3_f32 v35, v35, v18, v19
	v_max3_f32 v35, v35, v20, v21
	v_max3_f32 v35, v35, v22, v23
	v_max3_f32 v35, v35, v24, v25
	v_max3_f32 v35, v35, v26, v27
	v_max3_f32 v35, v35, v28, v29
	v_max3_f32 v35, v35, v30, v31
	v_max3_f32 v35, v35, v32, v33
	v_mov_b32_e32 v36, v35
	s_nop 1
	v_permlane32_swap_b32_e32 v35, v36
	v_max_f32_e32 v36, v36, v36
	v_max_f32_e32 v35, v35, v35
	v_max_f32_e32 v35, v35, v36
	v_add_f32_e32 v35, -4.0, v35
	v_sub_f32_e32 v2, v2, v35
	v_exp_f32_e32 v228, v2
	v_sub_f32_e32 v2, v3, v35
	v_exp_f32_e32 v229, v2
	v_sub_f32_e32 v2, v4, v35
	v_exp_f32_e32 v220, v2
	v_sub_f32_e32 v2, v5, v35
	v_exp_f32_e32 v221, v2
	v_sub_f32_e32 v2, v6, v35
	v_exp_f32_e32 v226, v2
	v_sub_f32_e32 v2, v7, v35
	v_exp_f32_e32 v227, v2
	v_sub_f32_e32 v2, v8, v35
	v_exp_f32_e32 v224, v2
	v_sub_f32_e32 v2, v9, v35
	v_exp_f32_e32 v225, v2
	v_sub_f32_e32 v2, v10, v35
	v_exp_f32_e32 v222, v2
	v_sub_f32_e32 v2, v11, v35
	v_exp_f32_e32 v223, v2
	v_sub_f32_e32 v2, v12, v35
	v_exp_f32_e32 v162, v2
	v_sub_f32_e32 v2, v13, v35
	v_exp_f32_e32 v163, v2
	v_sub_f32_e32 v2, v14, v35
	v_exp_f32_e32 v166, v2
	v_sub_f32_e32 v2, v15, v35
	v_exp_f32_e32 v167, v2
	v_sub_f32_e32 v2, v16, v35
	v_exp_f32_e32 v164, v2
	v_sub_f32_e32 v2, v17, v35
	v_exp_f32_e32 v165, v2
	v_mov_b32_e32 v14, v1
	v_mov_b32_e32 v15, v1
	v_sub_f32_e32 v127, v33, v35
	v_sub_f32_e32 v126, v32, v35
	v_sub_f32_e32 v125, v31, v35
	v_sub_f32_e32 v124, v30, v35
	v_sub_f32_e32 v123, v29, v35
	v_sub_f32_e32 v122, v28, v35
	v_sub_f32_e32 v121, v27, v35
	v_sub_f32_e32 v120, v26, v35
	v_sub_f32_e32 v119, v25, v35
	v_sub_f32_e32 v118, v24, v35
	v_sub_f32_e32 v117, v23, v35
	v_sub_f32_e32 v116, v22, v35
	v_sub_f32_e32 v115, v21, v35
	v_sub_f32_e32 v114, v20, v35
	v_sub_f32_e32 v113, v19, v35
	v_sub_f32_e32 v112, v18, v35
	v_sub_f32_e32 v96, 4.0, v35
	v_mov_b32_e32 v2, v1
	v_mov_b32_e32 v3, v1
	v_mov_b32_e32 v4, v1
	v_mov_b32_e32 v5, v1
	v_mov_b32_e32 v6, v1
	v_mov_b32_e32 v7, v1
	v_mov_b32_e32 v8, v1
	v_mov_b32_e32 v9, v1
	v_mov_b32_e32 v10, v1
	v_mov_b32_e32 v11, v1
	v_mov_b32_e32 v12, v1
	v_mov_b32_e32 v13, v1
	v_mov_b64_e32 v[78:79], v[14:15]
	v_mov_b64_e32 v[62:63], v[14:15]
	v_mov_b64_e32 v[46:47], v[14:15]
	v_mov_b64_e32 v[30:31], v[14:15]
	v_mov_b64_e32 v[94:95], v[14:15]
	v_mov_b32_e32 v97, v96
	v_mov_b32_e32 v98, v96
	v_mov_b32_e32 v99, v96
	v_mov_b32_e32 v100, v96
	v_mov_b32_e32 v101, v96
	v_mov_b32_e32 v102, v96
	v_mov_b32_e32 v103, v96
	v_mov_b32_e32 v104, v96
	v_mov_b32_e32 v105, v96
	v_mov_b32_e32 v106, v96
	v_mov_b32_e32 v107, v96
	v_mov_b32_e32 v108, v96
	v_mov_b32_e32 v109, v96
	v_mov_b32_e32 v110, v96
	v_mov_b32_e32 v111, v96
	v_mov_b64_e32 v[76:77], v[12:13]
	v_mov_b64_e32 v[74:75], v[10:11]
	v_mov_b64_e32 v[72:73], v[8:9]
	v_mov_b64_e32 v[70:71], v[6:7]
	v_mov_b64_e32 v[68:69], v[4:5]
	v_mov_b64_e32 v[66:67], v[2:3]
	v_mov_b64_e32 v[64:65], v[0:1]
	v_mov_b64_e32 v[60:61], v[12:13]
	v_mov_b64_e32 v[58:59], v[10:11]
	v_mov_b64_e32 v[56:57], v[8:9]
	v_mov_b64_e32 v[54:55], v[6:7]
	v_mov_b64_e32 v[52:53], v[4:5]
	v_mov_b64_e32 v[50:51], v[2:3]
	v_mov_b64_e32 v[48:49], v[0:1]
	v_mov_b64_e32 v[44:45], v[12:13]
	v_mov_b64_e32 v[42:43], v[10:11]
	v_mov_b64_e32 v[40:41], v[8:9]
	v_mov_b64_e32 v[38:39], v[6:7]
; __device__ __forceinline__ void attn_unit(const unsigned char* __restrict__ Qb, const unsigned char* __restrict__ Kh, const unsigned char* __restrict__ VTh, f16* __restrict__ Ob, int seq, LAS char* lds) {
;     ...
;     f32x16 o[5] = {}; v8i qf[3]; f32x16 negm;
	v_mov_b64_e32 v[36:37], v[4:5]
	v_mov_b64_e32 v[34:35], v[2:3]
	v_mov_b64_e32 v[32:33], v[0:1]
	v_mov_b64_e32 v[28:29], v[12:13]
	v_mov_b64_e32 v[26:27], v[10:11]
	v_mov_b64_e32 v[24:25], v[8:9]
	v_mov_b64_e32 v[22:23], v[6:7]
	v_mov_b64_e32 v[20:21], v[4:5]
	v_mov_b64_e32 v[18:19], v[2:3]
	v_mov_b64_e32 v[16:17], v[0:1]
	v_mov_b64_e32 v[92:93], v[12:13]
	v_mov_b64_e32 v[90:91], v[10:11]
	v_mov_b64_e32 v[88:89], v[8:9]
	v_mov_b64_e32 v[86:87], v[6:7]
	v_mov_b64_e32 v[84:85], v[4:5]
	v_mov_b64_e32 v[82:83], v[2:3]
	v_mov_b64_e32 v[80:81], v[0:1]
	v_lshlrev_b32_e32 v2, 4, v216
	v_and_b32_e32 v2, 0x3f0, v2
	v_or_b32_e32 v3, 0xffffe000, v2
	v_add_u32_e32 v4, s17, v3
	s_mov_b32 s0, 0xaaaaaaab
	v_mul_hi_u32 v5, v4, s0
	v_lshrrev_b32_e32 v6, 7, v5
	s_movk_i32 s0, 0xc0
	v_mul_lo_u32 v7, v6, s0
	v_add_u32_e32 v6, s22, v6
	s_movk_i32 s0, 0x300
	v_lshrrev_b32_e32 v5, 5, v5
	v_sub_u32_e32 v4, v4, v7
	v_mul_lo_u32 v6, v6, s0
	v_and_b32_e32 v5, 48, v5
	v_bitop3_b32 v4, v5, v6, v4 bitop3:0xde
	v_or_b32_e32 v8, s28, v2
	v_cndmask_b32_e64 v12, v8, v4, s[56:57]
	v_add_u32_e32 v4, s19, v3
	s_mov_b32 s0, 0xaaaaaaab
	v_mul_hi_u32 v5, v4, s0
	v_lshrrev_b32_e32 v6, 7, v5
	s_movk_i32 s0, 0xc0
	v_mul_lo_u32 v7, v6, s0
	v_add_u32_e32 v6, s34, v6
	s_movk_i32 s0, 0x300
	v_lshrrev_b32_e32 v5, 5, v5
	v_sub_u32_e32 v4, v4, v7
	v_mul_lo_u32 v6, v6, s0
	v_and_b32_e32 v5, 48, v5
	v_bitop3_b32 v4, v5, v6, v4 bitop3:0xde
	v_or_b32_e32 v8, s35, v2
	v_cndmask_b32_e64 v13, v4, v8, s[4:5]
	v_add_u32_e32 v4, s46, v3
	s_mov_b32 s0, 0xaaaaaaab
	v_mul_hi_u32 v5, v4, s0
	v_lshrrev_b32_e32 v6, 7, v5
	s_movk_i32 s0, 0xc0
	v_mul_lo_u32 v7, v6, s0
	v_add_u32_e32 v6, s3, v6
	s_movk_i32 s0, 0x300
	v_lshrrev_b32_e32 v5, 5, v5
	v_sub_u32_e32 v4, v4, v7
	v_mul_lo_u32 v6, v6, s0
	v_and_b32_e32 v5, 48, v5
	v_bitop3_b32 v4, v5, v6, v4 bitop3:0xde
	v_or_b32_e32 v8, s26, v2
	v_cndmask_b32_e64 v14, v4, v8, s[6:7]
	v_add_u32_e32 v4, s50, v3
	s_mov_b32 s0, 0xaaaaaaab
	v_mul_hi_u32 v5, v4, s0
	v_lshrrev_b32_e32 v6, 7, v5
	s_movk_i32 s0, 0xc0
	v_mul_lo_u32 v7, v6, s0
	v_add_u32_e32 v6, s30, v6
	s_movk_i32 s0, 0x300
	v_lshrrev_b32_e32 v5, 5, v5
	v_sub_u32_e32 v4, v4, v7
	v_mul_lo_u32 v6, v6, s0
	v_and_b32_e32 v5, 48, v5
	v_bitop3_b32 v4, v5, v6, v4 bitop3:0xde
	v_or_b32_e32 v8, s31, v2
	v_cndmask_b32_e64 v15, v4, v8, s[8:9]
	v_add_u32_e32 v4, s51, v3
	s_mov_b32 s0, 0xaaaaaaab
	v_mul_hi_u32 v5, v4, s0
	v_lshrrev_b32_e32 v6, 7, v5
	s_movk_i32 s0, 0xc0
	v_mul_lo_u32 v7, v6, s0
	v_add_u32_e32 v6, s16, v6
	s_movk_i32 s0, 0x300
	v_lshrrev_b32_e32 v5, 5, v5
	v_sub_u32_e32 v4, v4, v7
	v_mul_lo_u32 v6, v6, s0
	v_and_b32_e32 v5, 48, v5
	v_bitop3_b32 v4, v5, v6, v4 bitop3:0xde
	v_or_b32_e32 v8, s18, v2
	v_cndmask_b32_e64 v9, v4, v8, s[10:11]
	v_mov_b32_e32 v5, 0x19000
	v_lshl_add_u32 v6, v216, 4, v5
	v_lshl_add_u32 v7, v216, 2, v5
	ds_write_b128 v6, v[12:15]
	ds_write_b32 v7, v9 offset:8192
	s_bitcmp1_b32 s15, 0
	s_cselect_b32 s1, 0x6000, 0
	v_add_u32_e32 v12, s1, v244
	v_add_u32_e32 v13, s1, v245
	v_add_u32_e32 v14, 0xf000, v12
	v_add_u32_e32 v15, 0xf000, v13
	ds_read_b128 v[202:205], v12 offset:61440
	ds_read_b128 v[206:209], v13 offset:61440
	ds_read_b128 v[194:197], v14 offset:6144
	ds_read_b128 v[198:201], v15 offset:6144
	v_add_f32_e32 v80, v80, v228
	v_add_f32_e32 v81, v81, v229
	v_add_f32_e32 v82, v82, v220
	v_add_f32_e32 v83, v83, v221
	v_add_f32_e32 v80, v80, v226
	v_add_f32_e32 v81, v81, v227
	v_add_f32_e32 v82, v82, v224
	v_add_f32_e32 v83, v83, v225
	v_add_f32_e32 v80, v80, v222
	v_add_f32_e32 v81, v81, v223
	v_add_f32_e32 v82, v82, v162
	v_add_f32_e32 v83, v83, v163
	v_add_f32_e32 v80, v80, v166
	v_add_f32_e32 v81, v81, v167
	v_add_f32_e32 v82, v82, v164
	v_add_f32_e32 v83, v83, v165
	s_mov_b32 s82, 0xffff3000
	s_mov_b32 s83, 0xffff4000
	s_branch .LBB0_589

; #define LAS __attribute__((address_space(3)))
; #define SBAR() __builtin_amdgcn_sched_barrier(0)
; #define MFMA8(A, B, C) __builtin_amdgcn_mfma_scale_f32_32x32x64_f8f6f4(A, B, C, 0, 0, 0, 0x7F7F7F7F, 0, 0x7F7F7F7F)
; template <bool FIRST>
; __device__ __forceinline__ void partialSM(f32x16& p0, f32x16& p1, f32x16& negm, float& dl, float& alpha) {
;     ...
;     for (int r = 0; r < 16; ++r) p0[r] = __builtin_amdgcn_exp2f(p0[r]);
; }
; __device__ __forceinline__ void finishSM(f32x16& p0, f32x16& p1, v8i& pa) {
; #pragma unroll
;     for (int r = 0; r < 16; ++r) p1[r] = __builtin_amdgcn_exp2f(p1[r]);
; #pragma unroll
;     for (int w = 0; w < 4; ++w) { pa[w] = (int)pk4_fp8(p0[4 * w], p0[4 * w + 1], p0[4 * w + 2], p0[4 * w + 3]); pa[4 + w] = (int)pk4_fp8(p1[4 * w], p1[4 * w + 1], p1[4 * w + 2], p1[4 * w + 3]); }
; }
; __device__ __forceinline__ v8i ld32(const LAS char* a0, const LAS char* a1) { const v4i x = *(const LAS v4i*)a0, y = *(const LAS v4i*)a1; return (v8i){x[0], x[1], x[2], x[3], y[0], y[1], y[2], y[3]}; }
; __device__ __forceinline__ void qkt(f32x16& p0, f32x16& p1, const LAS char* Ks, int ka0, int ka1, const v8i* qf, const f32x16& negm) {
; #pragma unroll
;     for (int st = 0; st < 3; ++st) {
;         const v8i k0 = ld32(Ks + ka0 + 64 * st, Ks + ka1 + 64 * st), k1 = ld32(Ks + ka0 + 64 * st + 32 * 192, Ks + ka1 + 64 * st + 32 * 192);
;         if (st == 0) { p0 = MFMA8QK(k0, qf[st], negm); p1 = MFMA8QK(k1, qf[st], negm); }
;         else { p0 = MFMA8QK(k0, qf[st], p0); p1 = MFMA8QK(k1, qf[st], p1); } }
; }
; __device__ __forceinline__ void pv_d0(f32x16* o, const LAS char* Vs, int va0, int va1, v8i pa) {
; #pragma unroll
;     for (int d0 = 0; d0 < 4; ++d0) { const v8i vf = ld32(Vs + va0 + 2048 * d0, Vs + va1 + 2048 * d0); o[d0] = MFMA8(pa, vf, o[d0]); }
;     const v8i ones = {0x38383838, 0x38383838, 0x38383838, 0x38383838, 0x38383838, 0x38383838, 0x38383838, 0x38383838};
;     o[4] = MFMA8(pa, ones, o[4]);
; __device__ __forceinline__ void attn_unit(const unsigned char* __restrict__ Qb, const unsigned char* __restrict__ Kh, const unsigned char* __restrict__ VTh, f16* __restrict__ Ob, int seq, LAS char* lds) {
;     ...
;         SBAR(); qkt(pB0, pB1, KSL(j), ka0, ka1, qf, negm);
;         finishSM(pA0, pA1, pa); SBAR();
;         pv_d0(o, VSL(j - 1), va0, va1, pa); partialSM<false>(pB0, pB1, negm, dlB, alB);
;         WBAR();
.LBB0_589:
	s_bitcmp1_b32 s15, 0
	s_cselect_b32 s0, 0x6000, 0
	s_add_i32 s0, s0, 0
	v_add_u32_e32 v0, s0, v244
	v_add_u32_e32 v210, s0, v245
	v_add_u32_e32 v211, 0xf000, v0
	v_add_u32_e32 v212, 0xf000, v210
	ds_read_b128 v[2:5], v0 offset:61504
	ds_read_b128 v[6:9], v210 offset:61504
	v_exp_f32_e32 v112, v112
	v_exp_f32_e32 v113, v113
	v_exp_f32_e32 v114, v114
	v_exp_f32_e32 v115, v115
	s_waitcnt lgkmcnt(4)
	v_mfma_scale_f32_32x32x64_f8f6f4 v[144:159], v[202:209], v[184:191], v[96:111], v234, v233 op_sel_hi:[0,0,0]
	ds_read_b128 v[202:205], v211 offset:6208
	ds_read_b128 v[206:209], v212 offset:6208
	v_exp_f32_e32 v116, v116
	v_exp_f32_e32 v117, v117
	v_exp_f32_e32 v118, v118
	v_exp_f32_e32 v119, v119
	v_exp_f32_e32 v120, v120
	v_exp_f32_e32 v121, v121
	s_waitcnt lgkmcnt(4)
	v_mfma_scale_f32_32x32x64_f8f6f4 v[128:143], v[194:201], v[184:191], v[96:111], v234, v233 op_sel_hi:[0,0,0]
	ds_read_b128 v[194:197], v0 offset:61568
	ds_read_b128 v[198:201], v210 offset:61568
	v_exp_f32_e32 v122, v122
	v_exp_f32_e32 v123, v123
	v_exp_f32_e32 v124, v124
	v_exp_f32_e32 v125, v125
	v_exp_f32_e32 v126, v126
	v_exp_f32_e32 v127, v127
	s_waitcnt lgkmcnt(4)
	v_mfma_scale_f32_32x32x64_f8f6f4 v[144:159], v[2:9], v[176:183], v[144:159], v234, v233 op_sel_hi:[0,0,0]
	ds_read_b128 v[2:5], v211 offset:6272
	ds_read_b128 v[6:9], v212 offset:6272
	v_add_f32_e32 v80, v80, v112
	v_add_f32_e32 v81, v81, v113
	v_add_f32_e32 v82, v82, v114
	v_add_f32_e32 v83, v83, v115
	v_add_f32_e32 v80, v80, v116
	v_add_f32_e32 v81, v81, v117
	v_add_f32_e32 v82, v82, v118
	v_add_f32_e32 v83, v83, v119
	v_add_f32_e32 v80, v80, v120
	v_add_f32_e32 v81, v81, v121
	v_add_f32_e32 v82, v82, v122
	v_add_f32_e32 v83, v83, v123
	s_waitcnt lgkmcnt(4)
	v_mfma_scale_f32_32x32x64_f8f6f4 v[128:143], v[202:209], v[176:183], v[128:143], v234, v233 op_sel_hi:[0,0,0]
	v_add_f32_e32 v80, v80, v124
	v_add_f32_e32 v81, v81, v125
	v_add_f32_e32 v82, v82, v126
	v_add_f32_e32 v83, v83, v127
	v_cvt_pk_fp8_f32 v117, v116, v117
	v_cvt_pk_fp8_f32 v116, v112, v113
	v_cvt_pk_fp8_f32 v117, v118, v119 op_sel:[0,0,1]
	v_cvt_pk_fp8_f32 v118, v120, v121
	s_waitcnt lgkmcnt(2)
	v_mfma_scale_f32_32x32x64_f8f6f4 v[144:159], v[194:201], v[168:175], v[144:159], v234, v233 op_sel_hi:[0,0,0]
	v_cvt_pk_fp8_f32 v119, v124, v125
	v_cvt_pk_fp8_f32 v116, v114, v115 op_sel:[0,0,1]
	v_cvt_pk_fp8_f32 v118, v122, v123 op_sel:[0,0,1]
	v_cvt_pk_fp8_f32 v119, v126, v127 op_sel:[0,0,1]
	v_cvt_pk_fp8_f32 v112, v228, v229
	v_cvt_pk_fp8_f32 v113, v226, v227
	s_waitcnt lgkmcnt(0)
	v_mfma_scale_f32_32x32x64_f8f6f4 v[128:143], v[2:9], v[168:175], v[128:143], v234, v233 op_sel_hi:[0,0,0]
	v_cvt_pk_fp8_f32 v114, v222, v223
	v_cvt_pk_fp8_f32 v115, v166, v167
	v_cvt_pk_fp8_f32 v112, v220, v221 op_sel:[0,0,1]
	v_cvt_pk_fp8_f32 v113, v224, v225 op_sel:[0,0,1]
	v_cvt_pk_fp8_f32 v114, v162, v163 op_sel:[0,0,1]
	v_cvt_pk_fp8_f32 v115, v164, v165 op_sel:[0,0,1]
	s_add_i32 s66, s21, -2
	s_ashr_i32 s38, s66, 1
	s_mul_hi_i32 s0, s38, 0x55555556
	s_lshr_b32 s1, s0, 31
	s_add_i32 s0, s0, s1
	s_mul_i32 s0, s0, 3
	s_sub_i32 s0, s38, s0
	s_lshl_b32 s0, s0, 14
	s_add_i32 s0, s0, 0
	v_add_u32_e32 v0, s0, v241
	v_add_u32_e32 v11, s0, v240
	ds_read_b128 v[208:211], v0
	ds_read_b128 v[212:215], v11
	ds_read_b128 v[200:203], v0 offset:2048
	ds_read_b128 v[204:207], v11 offset:2048
	ds_read_b128 v[192:195], v0 offset:4096
	ds_read_b128 v[196:199], v11 offset:4096
	ds_read_b128 v[2:5], v0 offset:6144
	ds_read_b128 v[6:9], v11 offset:6144
	v_mov_b32_e32 v125, 0x19000
	v_lshl_add_u32 v126, v216, 4, v125
	v_lshl_add_u32 v127, v216, 2, v125
	ds_read_b128 v[120:123], v126
	ds_read_b32 v124, v127 offset:8192
	v_max_f32_e32 v0, v145, v145
	v_max_f32_e32 v125, v144, v144
	v_max_f32_e32 v0, v125, v0
	v_max3_f32 v0, v0, v146, v147
	v_max3_f32 v0, v0, v148, v149
	v_max3_f32 v0, v0, v150, v151
	v_max3_f32 v0, v0, v152, v153
	v_max3_f32 v0, v0, v154, v155
	v_max3_f32 v0, v0, v156, v157
	v_max3_f32 v0, v0, v158, v159
	s_waitcnt lgkmcnt(8)
	v_mfma_scale_f32_32x32x64_f8f6f4 v[64:79], v[112:119], v[208:215], v[64:79], v234, v234 op_sel_hi:[0,0,0]
	v_exp_f32_e32 v14, v144
	v_exp_f32_e32 v15, v145
	v_exp_f32_e32 v10, v148
	v_exp_f32_e32 v11, v149
	v_max3_f32 v0, v0, v128, v129
	v_max3_f32 v0, v0, v130, v131
	v_max3_f32 v0, v0, v132, v133
	v_max3_f32 v0, v0, v134, v135
	v_add_f32_e32 v80, v80, v14
	v_add_f32_e32 v81, v81, v15
	v_add_f32_e32 v82, v82, v10
	v_add_f32_e32 v83, v83, v11
	s_waitcnt lgkmcnt(6)
	v_mfma_scale_f32_32x32x64_f8f6f4 v[48:63], v[112:119], v[200:207], v[48:63], v234, v234 op_sel_hi:[0,0,0]
	v_exp_f32_e32 v12, v150
	v_exp_f32_e32 v13, v151
	v_max3_f32 v0, v0, v136, v137
	v_max3_f32 v0, v0, v138, v139
	v_max3_f32 v0, v0, v140, v141
	v_max3_f32 v0, v0, v142, v143
	v_add_f32_e32 v80, v80, v12
	v_add_f32_e32 v81, v81, v13
	s_waitcnt lgkmcnt(4)
	v_mfma_scale_f32_32x32x64_f8f6f4 v[32:47], v[112:119], v[192:199], v[32:47], v234, v234 op_sel_hi:[0,0,0]
	v_exp_f32_e32 v192, v146
	v_exp_f32_e32 v193, v147
	v_mov_b32_e32 v125, v0
	s_nop 1
	v_permlane32_swap_b32_e32 v0, v125
	v_max_f32_e32 v125, v125, v125
	v_max_f32_e32 v0, v0, v0
	v_add_f32_e32 v82, v82, v192
	v_add_f32_e32 v83, v83, v193
	s_waitcnt lgkmcnt(2)
	v_mfma_scale_f32_32x32x64_f8f6f4 v[16:31], v[112:119], v[2:9], v[16:31], v234, v234 op_sel_hi:[0,0,0]
	v_exp_f32_e32 v6, v152
	v_exp_f32_e32 v7, v153
	v_exp_f32_e32 v8, v154
	v_exp_f32_e32 v9, v155
	v_exp_f32_e32 v2, v156
	v_exp_f32_e32 v3, v157
	v_exp_f32_e32 v4, v158
	v_exp_f32_e32 v5, v159
	v_add_f32_e32 v80, v80, v6
	v_add_f32_e32 v81, v81, v7
	v_add_f32_e32 v82, v82, v8
	v_add_f32_e32 v83, v83, v9
	v_add_f32_e32 v80, v80, v2
	v_add_f32_e32 v81, v81, v3
	v_add_f32_e32 v82, v82, v4
	v_add_f32_e32 v83, v83, v5
	s_waitcnt vmcnt(0) lgkmcnt(0)
	s_barrier
; #define WBAR() do { asm volatile("s_waitcnt vmcnt(0) lgkmcnt(0)" ::: "memory"); __builtin_amdgcn_s_barrier(); asm volatile("" ::: "memory"); } while (0)
; #define FIX(a, dlt, P0, P1) do { if (__any((dlt) > 0.f)) { if (hi == 0) al_l[r32] = (a); asm volatile("s_waitcnt lgkmcnt(0)" ::: "memory"); \
;     _Pragma("unroll") for (int d = 0; d < 5; ++d) _Pragma("unroll") for (int r = 0; r < 16; ++r) o[d][r] *= al_l[crow(r, hi)]; \
;     _Pragma("unroll") for (int r = 0; r < 16; ++r) { P0[r] *= (a); P1[r] -= (dlt); negm[r] -= (dlt); } } } while (0)
; __device__ __forceinline__ void attn_unit(const unsigned char* __restrict__ Qb, const unsigned char* __restrict__ Kh, const unsigned char* __restrict__ VTh, f16* __restrict__ Ob, int seq, LAS char* lds) {
;     ...
;         WBAR();
;         { const int J = (j - 1) >> 1; if (J + 2 < NS) ISSUE(J + 2); }
;         FIX(alB, dlB, pB0, pB1);
	v_max_f32_e32 v0, v0, v125
	s_add_i32 s42, s38, 2
	v_cmp_ge_f32_e64 s[0:1], s67, v0
	s_cmp_ge_i32 s42, s14
	s_cbranch_scc1 .Lattn_noissue
	s_bitcmp1_b32 s21, 1
	s_cselect_b32 s44, 0x6000, 0
	v_add_u32_e32 v126, s44, v244
	v_add_u32_e32 v127, s44, v245
	ds_read_b128 v[208:211], v126 offset:49152
	ds_read_b128 v[212:215], v127 offset:49152
	s_ashr_i32 s43, s42, 31
	s_mul_i32 s38, s42, 0x18000
	s_mul_hi_i32 s39, s42, 0x18000
	s_add_u32 s38, s24, s38
	s_addc_u32 s39, s25, s39
	s_lshl_b64 s[40:41], s[42:43], 14
	s_add_u32 s40, s52, s40
	s_addc_u32 s41, s53, s41
	s_mul_hi_i32 s43, s42, 0x55555556
	s_lshr_b32 s67, s43, 31
	s_add_i32 s43, s43, s67
	s_mul_i32 s43, s43, 3
	s_sub_i32 s42, s42, s43
	s_lshl_b32 s67, s42, 14
	s_bitcmp1_b32 s66, 1
	s_mov_b32 s42, 0xa000
	s_cselect_b32 s66, 0x10000, s42
	s_add_i32 s42, s67, s28
	s_add_i32 s43, s29, s66
	s_and_b64 vcc, s[54:55], exec
	s_cselect_b32 s42, s42, s43
	s_mov_b32 m0, s42
	s_and_b64 vcc, exec, s[56:57]
	s_cselect_b32 s44, s38, s40
	s_cselect_b32 s45, s39, s41
	global_load_lds_dwordx4 v120, s[44:45]
	s_add_i32 s42, s67, s35
	s_add_i32 s43, s2, s66
	s_and_b64 vcc, s[58:59], exec
	s_cselect_b32 s42, s42, s43
	s_mov_b32 m0, s42
	s_and_b64 vcc, exec, s[4:5]
	s_cselect_b32 s44, s40, s38
	s_cselect_b32 s45, s41, s39
	global_load_lds_dwordx4 v121, s[44:45]
	s_add_i32 s42, s67, s26
	s_add_i32 s43, s27, s66
	s_and_b64 vcc, s[60:61], exec
	s_cselect_b32 s42, s42, s43
	s_mov_b32 m0, s42
	s_and_b64 vcc, exec, s[6:7]
	s_cselect_b32 s44, s40, s38
	s_cselect_b32 s45, s41, s39
	global_load_lds_dwordx4 v122, s[44:45]
	s_add_i32 s42, s67, s31
	s_add_i32 s43, s49, s66
	s_and_b64 vcc, s[62:63], exec
	s_cselect_b32 s42, s42, s43
	s_mov_b32 m0, s42
	s_and_b64 vcc, exec, s[8:9]
	s_cselect_b32 s44, s40, s38
	s_cselect_b32 s45, s41, s39
	global_load_lds_dwordx4 v123, s[44:45]
	s_add_i32 s42, s67, s18
	s_add_i32 s43, s33, s66
	s_and_b64 vcc, s[64:65], exec
	s_cselect_b32 s42, s42, s43
	s_mov_b32 m0, s42
	s_and_b64 vcc, exec, s[10:11]
	s_cselect_b32 s44, s40, s38
	s_cselect_b32 s45, s41, s39
	global_load_lds_dwordx4 v124, s[44:45]
	s_mov_b32 s67, 0x41000000
	ds_read_b128 v[120:123], v126 offset:55296
	ds_read_b128 v[124:127], v127 offset:55296
	v_add_f32_e32 v0, -4.0, v0
	s_cmp_lg_u64 s[0:1], exec
	v_max_f32_e32 v0, 0, v0
	s_cselect_b64 vcc, -1, 0
	v_cndmask_b32_e32 v0, 0, v0, vcc
	v_cmp_lt_f32_e32 vcc, 0, v0
	s_cbranch_vccz .LBB0_615
	s_branch .Lattn_fix1

; #define LAS __attribute__((address_space(3)))
; __device__ __forceinline__ unsigned pk4_fp8(float a, float b, float c, float d) { int w = 0; w = __builtin_amdgcn_cvt_pk_fp8_f32(a, b, w, false); w = __builtin_amdgcn_cvt_pk_fp8_f32(c, d, w, true); return (unsigned)w; }
; #define SBAR() __builtin_amdgcn_sched_barrier(0)
; #define MFMA8(A, B, C) __builtin_amdgcn_mfma_scale_f32_32x32x64_f8f6f4(A, B, C, 0, 0, 0, 0x7F7F7F7F, 0, 0x7F7F7F7F)
; __device__ __forceinline__ void finishSM(f32x16& p0, f32x16& p1, v8i& pa) {
; #pragma unroll
;     for (int r = 0; r < 16; ++r) p1[r] = __builtin_amdgcn_exp2f(p1[r]);
; #pragma unroll
;     for (int w = 0; w < 4; ++w) { pa[w] = (int)pk4_fp8(p0[4 * w], p0[4 * w + 1], p0[4 * w + 2], p0[4 * w + 3]); pa[4 + w] = (int)pk4_fp8(p1[4 * w], p1[4 * w + 1], p1[4 * w + 2], p1[4 * w + 3]); }
; }
; __device__ __forceinline__ v8i ld32(const LAS char* a0, const LAS char* a1) { const v4i x = *(const LAS v4i*)a0, y = *(const LAS v4i*)a1; return (v8i){x[0], x[1], x[2], x[3], y[0], y[1], y[2], y[3]}; }
; __device__ __forceinline__ void qkt(f32x16& p0, f32x16& p1, const LAS char* Ks, int ka0, int ka1, const v8i* qf, const f32x16& negm) {
; #pragma unroll
;     for (int st = 0; st < 3; ++st) {
;         const v8i k0 = ld32(Ks + ka0 + 64 * st, Ks + ka1 + 64 * st), k1 = ld32(Ks + ka0 + 64 * st + 32 * 192, Ks + ka1 + 64 * st + 32 * 192);
;         if (st == 0) { p0 = MFMA8QK(k0, qf[st], negm); p1 = MFMA8QK(k1, qf[st], negm); }
;         else { p0 = MFMA8QK(k0, qf[st], p0); p1 = MFMA8QK(k1, qf[st], p1); } }
; }
; __device__ __forceinline__ void pv_d0(f32x16* o, const LAS char* Vs, int va0, int va1, v8i pa) {
; #pragma unroll
;     for (int d0 = 0; d0 < 4; ++d0) { const v8i vf = ld32(Vs + va0 + 2048 * d0, Vs + va1 + 2048 * d0); o[d0] = MFMA8(pa, vf, o[d0]); }
;     const v8i ones = {0x38383838, 0x38383838, 0x38383838, 0x38383838, 0x38383838, 0x38383838, 0x38383838, 0x38383838};
;     o[4] = MFMA8(pa, ones, o[4]);
; __device__ __forceinline__ void attn_unit(const unsigned char* __restrict__ Qb, const unsigned char* __restrict__ Kh, const unsigned char* __restrict__ VTh, f16* __restrict__ Ob, int seq, LAS char* lds) {
;     ...
;         SBAR(); qkt(pA0, pA1, KSL(j + 1), ka0, ka1, qf, negm);
;         finishSM(pB0, pB1, pa); SBAR();
;         pv_d0(o, VSL(j), va0, va1, pa); partialSM<false>(pA0, pA1, negm, dlA, alA);
;         FIX(alA, dlA, pA0, pA1);
.LBB0_615:
	s_mul_hi_u32 s0, s15, 0xaaaaaaab
	s_lshr_b32 s0, s0, 1
	s_mul_i32 s0, s0, 0xffff4000
	s_bfe_i32 s1, s21, 0x10001
	s_and_b32 s1, s1, 0x6000
	s_add_i32 s1, s1, 0
	v_add_u32_e32 v0, s1, v244
	v_add_u32_e32 v161, s1, v245
	ds_read_b128 v[194:197], v0 offset:55360
	ds_read_b128 v[198:201], v161 offset:55360
	v_exp_f32_e32 v129, v129
	v_exp_f32_e32 v133, v133
	s_waitcnt lgkmcnt(4)
	v_mfma_scale_f32_32x32x64_f8f6f4 v[144:159], v[208:215], v[184:191], v[96:111], v234, v233 op_sel_hi:[0,0,0]
	ds_read_b128 v[202:205], v0 offset:49216
	ds_read_b128 v[206:209], v161 offset:49216
	v_exp_f32_e32 v130, v130
	v_exp_f32_e32 v131, v131
	v_exp_f32_e32 v134, v134
	v_exp_f32_e32 v135, v135
	v_exp_f32_e32 v136, v136
	v_exp_f32_e32 v137, v137
	v_exp_f32_e32 v140, v140
	v_exp_f32_e32 v141, v141
	v_exp_f32_e32 v138, v138
	v_exp_f32_e32 v139, v139
	v_exp_f32_e32 v142, v142
	v_exp_f32_e32 v143, v143
	v_exp_f32_e32 v128, v128
	v_exp_f32_e32 v132, v132
	s_waitcnt lgkmcnt(4)
	v_mfma_scale_f32_32x32x64_f8f6f4 v[112:127], v[120:127], v[184:191], v[96:111], v234, v233 op_sel_hi:[0,0,0]
	s_waitcnt lgkmcnt(2)
	v_mfma_scale_f32_32x32x64_f8f6f4 v[112:127], v[194:201], v[176:183], v[112:127], v234, v233 op_sel_hi:[0,0,0]
	s_waitcnt lgkmcnt(0)
	v_mfma_scale_f32_32x32x64_f8f6f4 v[144:159], v[202:209], v[176:183], v[144:159], v234, v233 op_sel_hi:[0,0,0]
	ds_read_b128 v[194:197], v0 offset:55424
	ds_read_b128 v[198:201], v161 offset:55424
	ds_read_b128 v[202:205], v0 offset:49280
	ds_read_b128 v[206:209], v161 offset:49280
	v_add_f32_e32 v80, v80, v128
	v_add_f32_e32 v81, v81, v129
	v_add_f32_e32 v82, v82, v130
	v_add_f32_e32 v83, v83, v131
	v_add_f32_e32 v80, v80, v132
	v_add_f32_e32 v81, v81, v133
	v_add_f32_e32 v82, v82, v134
	v_add_f32_e32 v83, v83, v135
	v_add_f32_e32 v80, v80, v136
	v_add_f32_e32 v81, v81, v137
	v_add_f32_e32 v82, v82, v138
	v_add_f32_e32 v83, v83, v139
	v_add_f32_e32 v80, v80, v140
	v_add_f32_e32 v81, v81, v141
	v_add_f32_e32 v82, v82, v142
	v_add_f32_e32 v83, v83, v143
	v_cvt_pk_fp8_f32 v133, v132, v133
	v_cvt_pk_fp8_f32 v132, v128, v129
	v_cvt_pk_fp8_f32 v133, v134, v135 op_sel:[0,0,1]
	v_cvt_pk_fp8_f32 v134, v136, v137
	v_cvt_pk_fp8_f32 v135, v140, v141
	s_waitcnt lgkmcnt(0)
	v_mfma_scale_f32_32x32x64_f8f6f4 v[112:127], v[194:201], v[168:175], v[112:127], v234, v233 op_sel_hi:[0,0,0]
	v_cvt_pk_fp8_f32 v132, v130, v131 op_sel:[0,0,1]
	v_cvt_pk_fp8_f32 v134, v138, v139 op_sel:[0,0,1]
	v_cvt_pk_fp8_f32 v135, v142, v143 op_sel:[0,0,1]
	v_cvt_pk_fp8_f32 v128, v14, v15
	v_cvt_pk_fp8_f32 v129, v10, v11
	v_cvt_pk_fp8_f32 v130, v6, v7
	v_cvt_pk_fp8_f32 v131, v2, v3
	v_cvt_pk_fp8_f32 v128, v192, v193 op_sel:[0,0,1]
	v_cvt_pk_fp8_f32 v129, v12, v13 op_sel:[0,0,1]
	v_cvt_pk_fp8_f32 v130, v8, v9 op_sel:[0,0,1]
	v_cvt_pk_fp8_f32 v131, v4, v5 op_sel:[0,0,1]
	v_or_b32_e32 v10, s0, v218
	v_or_b32_e32 v11, s0, v250
	v_add_u32_e32 v10, v247, v10
	v_add_u32_e32 v11, v247, v11
	ds_read_b128 v[2:5], v10
	ds_read_b128 v[6:9], v11
	v_mfma_scale_f32_32x32x64_f8f6f4 v[144:159], v[202:209], v[168:175], v[144:159], v234, v233 op_sel_hi:[0,0,0]
	ds_read_b128 v[194:197], v10 offset:2048
	ds_read_b128 v[198:201], v11 offset:2048
	s_waitcnt lgkmcnt(2)
	v_mfma_scale_f32_32x32x64_f8f6f4 v[64:79], v[128:135], v[2:9], v[64:79], v234, v234 op_sel_hi:[0,0,0]
	ds_read_b128 v[2:5], v10 offset:4096
	ds_read_b128 v[6:9], v11 offset:4096
	s_waitcnt lgkmcnt(2)
	v_mfma_scale_f32_32x32x64_f8f6f4 v[48:63], v[128:135], v[194:201], v[48:63], v234, v234 op_sel_hi:[0,0,0]
	ds_read_b128 v[194:197], v10 offset:6144
	ds_read_b128 v[198:201], v11 offset:6144
	s_nop 7
	s_nop 1
	v_exp_f32_e32 v228, v144
	v_exp_f32_e32 v229, v145
	v_exp_f32_e32 v220, v146
	v_exp_f32_e32 v221, v147
	v_exp_f32_e32 v226, v148
	v_exp_f32_e32 v227, v149
	v_exp_f32_e32 v224, v150
	v_exp_f32_e32 v225, v151
	v_exp_f32_e32 v222, v152
	v_exp_f32_e32 v223, v153
	v_max_f32_e32 v0, v145, v145
	v_add_f32_e32 v80, v80, v228
	v_add_f32_e32 v81, v81, v229
	v_add_f32_e32 v82, v82, v220
	v_add_f32_e32 v83, v83, v221
	v_add_f32_e32 v80, v80, v226
	v_add_f32_e32 v81, v81, v227
	v_add_f32_e32 v82, v82, v224
	v_add_f32_e32 v83, v83, v225
	v_add_f32_e32 v80, v80, v222
	v_add_f32_e32 v81, v81, v223
	s_waitcnt lgkmcnt(2)
	v_mfma_scale_f32_32x32x64_f8f6f4 v[32:47], v[128:135], v[2:9], v[32:47], v234, v234 op_sel_hi:[0,0,0]
	v_max_f32_e32 v2, v144, v144
	v_max_f32_e32 v0, v2, v0
	v_max3_f32 v0, v0, v146, v147
	v_max3_f32 v0, v0, v148, v149
	v_max3_f32 v0, v0, v150, v151
	v_max3_f32 v0, v0, v152, v153
	v_max3_f32 v0, v0, v154, v155
	v_max3_f32 v0, v0, v156, v157
	v_max3_f32 v0, v0, v158, v159
	s_waitcnt lgkmcnt(0)
	v_mfma_scale_f32_32x32x64_f8f6f4 v[16:31], v[128:135], v[194:201], v[16:31], v234, v234 op_sel_hi:[0,0,0]
	s_bitcmp0_b32 s15, 0
	s_cselect_b32 s1, 0x6000, 0
	v_add_u32_e32 v12, s1, v244
	v_add_u32_e32 v13, s1, v245
	v_add_u32_e32 v14, 0xf000, v12
	v_add_u32_e32 v15, 0xf000, v13
	ds_read_b128 v[202:205], v12 offset:61440
	ds_read_b128 v[206:209], v13 offset:61440
	ds_read_b128 v[194:197], v14 offset:6144
	ds_read_b128 v[198:201], v15 offset:6144
	v_max3_f32 v0, v0, v112, v113
	v_max3_f32 v0, v0, v114, v115
	v_max3_f32 v0, v0, v116, v117
	v_max3_f32 v0, v0, v118, v119
	v_max3_f32 v0, v0, v120, v121
	v_max3_f32 v0, v0, v122, v123
	v_max3_f32 v0, v0, v124, v125
	v_max3_f32 v0, v0, v126, v127
	v_mov_b32_e32 v2, v0
	s_nop 1
	v_permlane32_swap_b32_e32 v0, v2
	v_max_f32_e32 v2, v2, v2
	v_max_f32_e32 v0, v0, v0
	v_max_f32_e32 v0, v0, v2
	v_cmp_ge_f32_e32 vcc, s67, v0
	v_add_f32_e32 v0, -4.0, v0
	s_cmp_lg_u64 vcc, exec
	v_exp_f32_e32 v162, v154
	v_exp_f32_e32 v163, v155
	v_exp_f32_e32 v166, v156
	v_exp_f32_e32 v167, v157
	v_exp_f32_e32 v164, v158
	v_exp_f32_e32 v165, v159
	v_max_f32_e32 v0, 0, v0
	v_add_f32_e32 v80, v80, v162
	v_add_f32_e32 v81, v81, v163
	v_add_f32_e32 v82, v82, v166
	v_add_f32_e32 v83, v83, v167
	v_add_f32_e32 v80, v80, v164
	v_add_f32_e32 v81, v81, v165
	s_cselect_b64 vcc, -1, 0
	v_cndmask_b32_e32 v2, 0, v0, vcc
	v_cmp_lt_f32_e32 vcc, 0, v2
	s_cbranch_vccz .LBB0_588
	v_exp_f32_e64 v0, -v2
	s_and_saveexec_b64 s[0:1], s[12:13]
	s_cbranch_execz .LBB0_587
	ds_write_b32 v243, v0 offset:128
	s_branch .LBB0_587
